# hot loop heads (attention and GEMM K-loops) aligned to 64 bytes
# baseline (speedup 1.0000x reference)
.LBB0_41:
	s_nop 1
	v_sub_co_u32_e64 v0, s[16:17], s3, 64
	s_and_b64 s[16:17], s[16:17], exec
	v_readfirstlane_b32 s8, v0
	v_mov_b32_e32 v80, v220
	s_cselect_b32 s8, s3, s8
	s_cselect_b32 s10, 0, 8
	v_ashrrev_i32_e32 v16, 6, v80
	s_bfe_u32 s17, s8, 0x50003
	v_bfe_u32 v17, v80, 3, 3
	v_lshlrev_b32_e32 v18, 5, v16
	v_bfe_u32 v19, v80, 4, 2
	s_add_i32 s18, s8, s10
	s_lshl_b32 s8, s17, 7
	v_or_b32_e32 v1, v18, v17
	v_xor_b32_e32 v0, v19, v80
	v_add_u32_e32 v2, s8, v1
	s_movk_i32 s13, 0xb00
	v_lshlrev_b32_e32 v0, 3, v0
	s_lshl_b32 s19, s17, 13
	s_lshl_b32 s42, s18, 10
	v_mul_lo_u32 v2, v2, s13
	v_and_b32_e32 v20, 56, v0
	v_or_b32_e32 v3, 8, v1
	s_sub_i32 s10, s42, s19
	v_or_b32_e32 v192, v2, v20
	v_lshrrev_b32_e32 v2, 1, v3
	s_or_b32 s10, s10, s31
	v_xor_b32_e32 v2, v2, v80
	v_add_u32_e32 v4, s8, v3
	v_lshlrev_b32_e32 v2, 3, v2
	v_add_u32_e32 v3, s10, v3
	v_mul_lo_u32 v4, v4, s13
	v_and_b32_e32 v21, 56, v2
	v_mul_lo_u32 v3, v3, s13
	v_or_b32_e32 v2, v21, v4
	v_or_b32_e32 v4, v21, v3
	v_or_b32_e32 v3, 16, v1
	v_add_u32_e32 v5, s8, v3
	v_add_u32_e32 v3, s10, v3
	v_add_u32_e32 v0, s10, v1
	v_mul_lo_u32 v3, v3, s13
	v_or_b32_e32 v1, 24, v1
	v_or_b32_e32 v8, v3, v20
	v_lshrrev_b32_e32 v3, 1, v1
	v_mul_lo_u32 v5, v5, s13
	v_xor_b32_e32 v3, v3, v80
	v_or_b32_e32 v6, v5, v20
	v_add_u32_e32 v5, s8, v1
	v_lshlrev_b32_e32 v3, 3, v3
	v_add_u32_e32 v1, s10, v1
	s_cmp_lg_u32 32, -1
	v_and_b32_e32 v22, 56, v3
	v_mul_lo_u32 v1, v1, s13
	v_lshlrev_b32_e32 v23, 12, v16
	s_cselect_b32 s43, 32, 0
	v_ashrrev_i32_e32 v3, 1, v80
	v_or_b32_e32 v12, v22, v1
	v_add_u32_e32 v82, s43, v23
	v_and_b32_e32 v1, 15, v80
	v_and_b32_e32 v81, 0xffffffc0, v3
	s_add_i32 s44, s43, 0x4000
	v_mul_lo_u32 v0, v0, s13
	v_or_b32_e32 v24, v81, v1
	v_lshlrev_b32_e32 v1, 7, v80
	v_add_u32_e32 v3, s44, v23
	v_readfirstlane_b32 s44, v82
	v_readlane_b32 s88, v252, 11
	v_or_b32_e32 v0, v0, v20
	v_and_b32_e32 v83, 0x2780, v1
	v_lshl_add_u64 v[14:15], v[192:193], 1, s[28:29]
	s_mov_b32 m0, s44
	v_mov_b32_e32 v1, v193
	v_readlane_b32 s89, v252, 12
	v_readfirstlane_b32 s44, v3
	global_load_lds_dwordx4 v[14:15], off
	v_lshl_add_u64 v[0:1], v[0:1], 1, s[88:89]
	s_mov_b32 m0, s44
	v_mov_b32_e32 v3, v193
	s_add_i32 s44, s43, 0x400
	global_load_lds_dwordx4 v[0:1], off
	v_lshl_add_u64 v[0:1], v[2:3], 1, s[28:29]
	v_add_u32_e32 v2, s44, v23
	v_mul_lo_u32 v5, v5, s13
	v_readfirstlane_b32 s44, v2
	s_mov_b32 m0, s44
	s_add_i32 s44, s43, 0x4400
	v_add_u32_e32 v2, s44, v23
	global_load_lds_dwordx4 v[0:1], off
	v_readfirstlane_b32 s44, v2
	s_mov_b32 m0, s44
	s_add_i32 s44, s43, 0x800
	v_or_b32_e32 v10, v22, v5
	v_mov_b32_e32 v5, v193
	v_add_u32_e32 v2, s44, v23
	v_lshl_add_u64 v[0:1], v[4:5], 1, s[88:89]
	v_readfirstlane_b32 s44, v2
	global_load_lds_dwordx4 v[0:1], off
	s_mov_b32 m0, s44
	s_add_i32 s44, s43, 0x4800
	v_mov_b32_e32 v7, v193
	v_add_u32_e32 v2, s44, v23
	v_lshl_add_u64 v[0:1], v[6:7], 1, s[28:29]
	v_readfirstlane_b32 s44, v2
	global_load_lds_dwordx4 v[0:1], off
	s_mov_b32 m0, s44
	s_add_i32 s44, s43, 0xc00
	v_mov_b32_e32 v9, v193
	v_add_u32_e32 v2, s44, v23
	s_addk_i32 s43, 0x4c00
	v_lshl_add_u64 v[0:1], v[8:9], 1, s[88:89]
	v_mov_b32_e32 v11, v193
	v_readfirstlane_b32 s44, v2
	v_add_u32_e32 v2, s43, v23
	global_load_lds_dwordx4 v[0:1], off
	v_lshl_add_u64 v[0:1], v[10:11], 1, s[28:29]
	s_mov_b32 m0, s44
	v_mov_b32_e32 v13, v193
	v_readfirstlane_b32 s43, v2
	global_load_lds_dwordx4 v[0:1], off
	v_lshl_add_u64 v[0:1], v[12:13], 1, s[88:89]
	s_mov_b32 m0, s43
	s_mov_b32 s9, 0x16000
	global_load_lds_dwordx4 v[0:1], off
	v_bfe_u32 v0, v80, 1, 3
	v_xor_b32_e32 v1, v19, v0
	v_bitop3_b32 v0, v19, v0, 4 bitop3:0x36
	v_lshlrev_b32_e32 v84, 4, v0
	v_or_b32_e32 v0, s8, v17
	v_add_u32_e32 v0, v0, v18
	v_mul_lo_u32 v0, v0, s13
	v_lshlrev_b32_e32 v86, 4, v1
	v_or_b32_e32 v192, v0, v20
	s_mul_i32 s43, s17, 0x58000
	v_mul_lo_u32 v0, v16, s9
	v_mul_u32_u24_e32 v1, 0xb00, v17
	v_add3_u32 v2, v0, s43, v1
	v_or_b32_e32 v2, v2, v21
	s_add_i32 s44, s43, 0xb000
	v_lshl_add_u64 v[64:65], v[192:193], 1, s[40:41]
	v_add_u32_e32 v192, 0x5800, v2
	v_add3_u32 v2, s44, v0, v1
	s_add_i32 s43, s43, 0x10800
	v_lshl_add_u64 v[66:67], v[192:193], 1, s[40:41]
	v_or_b32_e32 v192, v2, v20
	v_add3_u32 v2, s43, v0, v1
	s_or_b32 s42, s42, s31
	v_lshl_add_u64 v[68:69], v[192:193], 1, s[40:41]
	v_or_b32_e32 v192, v2, v22
	v_add3_u32 v2, s42, v17, v18
	v_subrev_u32_e32 v2, s19, v2
	s_mul_i32 s18, s18, 0x2c0000
	v_readlane_b32 s9, v254, 28
	v_mul_lo_u32 v2, v2, s13
	s_add_i32 s19, s9, s18
	v_lshl_add_u64 v[70:71], v[192:193], 1, s[40:41]
	v_or_b32_e32 v192, v2, v20
	v_readlane_b32 s14, v254, 26
	v_add_u32_e32 v2, s19, v0
	v_readlane_b32 s9, v254, 29
	v_readlane_b32 s15, v254, 27
	v_add3_u32 v2, v2, v1, v21
	s_mul_i32 s17, s17, 0x1600000
	s_add_i32 s19, s9, s18
	v_readlane_b32 s9, v254, 30
	v_lshl_add_u64 v[72:73], v[192:193], 1, s[14:15]
	v_subrev_u32_e32 v192, s17, v2
	v_add_u32_e32 v2, s19, v0
	s_add_i32 s18, s9, s18
	v_add3_u32 v2, v2, v1, v20
	v_add_u32_e32 v0, s18, v0
	s_waitcnt vmcnt(0)
	v_lshl_add_u64 v[74:75], v[192:193], 1, s[14:15]
	v_subrev_u32_e32 v192, s17, v2
	v_add3_u32 v0, v0, v1, v22
	v_lshl_add_u64 v[76:77], v[192:193], 1, s[14:15]
	v_subrev_u32_e32 v192, s17, v0
	v_mov_b32_e32 v0, 0
	s_mov_b32 s16, 0
	v_lshlrev_b32_e32 v85, 7, v24
	v_lshl_add_u64 v[78:79], v[192:193], 1, s[14:15]
	s_mov_b64 s[42:43], 0
	v_mov_b32_e32 v1, v0
	v_mov_b32_e32 v2, v0
	v_mov_b32_e32 v3, v0
	v_mov_b32_e32 v4, v0
	v_mov_b32_e32 v5, v0
	v_mov_b32_e32 v6, v0
	v_mov_b32_e32 v7, v0
	v_mov_b32_e32 v8, v0
	v_mov_b32_e32 v9, v0
	v_mov_b32_e32 v10, v0
	v_mov_b32_e32 v11, v0
	v_mov_b32_e32 v12, v0
	v_mov_b32_e32 v13, v0
	v_mov_b32_e32 v14, v0
	v_mov_b32_e32 v15, v0
	v_mov_b32_e32 v16, v0
	v_mov_b32_e32 v17, v0
	v_mov_b32_e32 v18, v0
	v_mov_b32_e32 v19, v0
	v_mov_b32_e32 v20, v0
	v_mov_b32_e32 v21, v0
	v_mov_b32_e32 v22, v0
	v_mov_b32_e32 v23, v0
	v_mov_b32_e32 v24, v0
	v_mov_b32_e32 v25, v0
	v_mov_b32_e32 v26, v0
	v_mov_b32_e32 v27, v0
	v_mov_b32_e32 v28, v0
	v_mov_b32_e32 v29, v0
	v_mov_b32_e32 v30, v0
	v_mov_b32_e32 v31, v0
	v_mov_b32_e32 v32, v0
	v_mov_b32_e32 v33, v0
	v_mov_b32_e32 v34, v0
	v_mov_b32_e32 v35, v0
	v_mov_b32_e32 v36, v0
	v_mov_b32_e32 v37, v0
	v_mov_b32_e32 v38, v0
	v_mov_b32_e32 v39, v0
	v_mov_b32_e32 v40, v0
	v_mov_b32_e32 v41, v0
	v_mov_b32_e32 v42, v0
	v_mov_b32_e32 v43, v0
	v_mov_b32_e32 v44, v0
	v_mov_b32_e32 v45, v0
	v_mov_b32_e32 v46, v0
	v_mov_b32_e32 v47, v0
	v_mov_b32_e32 v48, v0
	v_mov_b32_e32 v49, v0
	v_mov_b32_e32 v50, v0
	v_mov_b32_e32 v51, v0
	v_mov_b32_e32 v52, v0
	v_mov_b32_e32 v53, v0
	v_mov_b32_e32 v54, v0
	v_mov_b32_e32 v55, v0
	v_mov_b32_e32 v56, v0
	v_mov_b32_e32 v57, v0
	v_mov_b32_e32 v58, v0
	v_mov_b32_e32 v59, v0
	v_mov_b32_e32 v60, v0
	v_mov_b32_e32 v61, v0
	v_mov_b32_e32 v62, v0
	v_mov_b32_e32 v63, v0
	v_readlane_b32 s90, v252, 13
	v_readlane_b32 s91, v252, 14
	v_readlane_b32 s92, v252, 15
	v_readlane_b32 s93, v252, 16
	v_readlane_b32 s94, v252, 17
	v_readlane_b32 s95, v252, 18
	s_waitcnt vmcnt(0) lgkmcnt(0)
	s_barrier
	v_add_u32_e32 v134, 32, v85
	v_add_u32_e32 v135, 32, v83
	v_add_u32_e32 v132, v134, v86
	v_add_u32_e32 v133, v135, v86
	ds_read_b128 v[88:91], v132
	ds_read_b128 v[96:99], v132 offset:2048
	ds_read_b128 v[104:107], v132 offset:4096
	ds_read_b128 v[112:115], v132 offset:6144
	ds_read_b128 v[92:95], v133 offset:16384
	ds_read_b128 v[100:103], v133 offset:18432
	ds_read_b128 v[108:111], v133 offset:20480
	ds_read_b128 v[116:119], v133 offset:22528
	v_readfirstlane_b32 s98, v64
	v_readfirstlane_b32 s99, v65
	v_readfirstlane_b32 s100, v72
	v_readfirstlane_b32 s101, v73
	s_sub_u32 s98, s98, 0x80
	s_subb_u32 s99, s99, 0
	s_sub_u32 s100, s100, 0x80
	s_subb_u32 s101, s101, 0
	v_subrev_u32_e32 v64, s98, v64
	v_subrev_u32_e32 v66, s98, v66
	v_subrev_u32_e32 v68, s98, v68
	v_subrev_u32_e32 v70, s98, v70
	v_subrev_u32_e32 v72, s100, v72
	v_subrev_u32_e32 v74, s100, v74
	v_subrev_u32_e32 v76, s100, v76
	v_subrev_u32_e32 v78, s100, v78
	v_add_u32_e32 v128, 0x8000, v82
	s_nop 0
	v_readfirstlane_b32 s18, v128
	s_nop 1
	s_mov_b32 m0, s18
	s_nop 0
	global_load_lds_dwordx4 v64, s[98:99]
	s_add_i32 m0, s18, 0x4000
	s_nop 0
	global_load_lds_dwordx4 v72, s[100:101]
	s_add_i32 m0, s18, 0x400
	s_nop 0
	global_load_lds_dwordx4 v66, s[98:99]
	s_add_i32 m0, s18, 0x4400
	s_nop 0
	global_load_lds_dwordx4 v74, s[100:101]
	s_add_i32 m0, s18, 0x800
	s_nop 0
	global_load_lds_dwordx4 v68, s[98:99]
	s_add_i32 m0, s18, 0x4800
	s_nop 0
	global_load_lds_dwordx4 v76, s[100:101]
	s_add_i32 m0, s18, 0xc00
	s_nop 0
	global_load_lds_dwordx4 v70, s[98:99]
	s_add_i32 m0, s18, 0x4c00
	s_nop 0
	global_load_lds_dwordx4 v78, s[100:101]
	s_add_u32 s42, s42, 0x80
	s_addc_u32 s43, s43, 0
	s_add_u32 s98, s98, 0x80
	s_addc_u32 s99, s99, 0
	s_add_u32 s100, s100, 0x80
	s_addc_u32 s101, s101, 0
	.p2align 6

.LBB0_63:
	s_min_i32 s8, s12, 8
	s_mul_i32 s42, s8, 44
	s_mov_b32 s19, s16
	s_add_i32 s18, s18, 8
	s_add_i32 s12, s12, -8
	s_add_i32 s17, s17, -8
	s_sub_i32 s16, s16, s42
	s_cmp_ge_i32 s19, s42
	s_cbranch_scc1 .LBB0_63
	s_lshl_b32 s12, s8, 3
	s_abs_i32 s16, s12
	v_cvt_f32_u32_e32 v0, s16
	s_sub_i32 s44, 0, s16
	s_abs_i32 s43, s19
	s_xor_b32 s42, s19, s12
	v_rcp_iflag_f32_e32 v0, v0
	s_ashr_i32 s42, s42, 31
	v_mov_b32_e32 v80, v220
	v_mul_f32_e32 v0, 0x4f7ffffe, v0
	v_cvt_u32_f32_e32 v0, v0
	v_ashrrev_i32_e32 v16, 6, v80
	v_bfe_u32 v19, v80, 4, 2
	v_bfe_u32 v17, v80, 3, 3
	v_readfirstlane_b32 s45, v0
	s_mul_i32 s44, s44, s45
	s_mul_hi_u32 s44, s45, s44
	s_add_i32 s45, s45, s44
	s_mul_hi_u32 s44, s43, s45
	s_mul_i32 s45, s44, s16
	s_sub_i32 s43, s43, s45
	s_add_i32 s46, s44, 1
	s_sub_i32 s45, s43, s16
	s_cmp_ge_u32 s43, s16
	s_cselect_b32 s44, s46, s44
	s_cselect_b32 s43, s45, s43
	s_add_i32 s45, s44, 1
	s_cmp_ge_u32 s43, s16
	s_cselect_b32 s43, s45, s44
	s_abs_i32 s44, s8
	v_cvt_f32_u32_e32 v0, s44
	s_xor_b32 s43, s43, s42
	s_sub_i32 s45, 0, s44
	s_sub_i32 s46, s43, s42
	v_rcp_iflag_f32_e32 v0, v0
	s_mul_i32 s12, s46, s12
	s_sub_i32 s12, s19, s12
	s_abs_i32 s48, s12
	v_mul_f32_e32 v0, 0x4f7ffffe, v0
	v_cvt_u32_f32_e32 v0, v0
	s_xor_b32 s47, s12, s8
	s_ashr_i32 s47, s47, 31
	v_lshlrev_b32_e32 v18, 5, v16
	v_readfirstlane_b32 s49, v0
	s_mul_i32 s45, s45, s49
	s_mul_hi_u32 s45, s49, s45
	s_add_i32 s49, s49, s45
	s_mul_hi_u32 s45, s48, s49
	s_mul_i32 s49, s45, s44
	s_sub_i32 s48, s48, s49
	s_add_i32 s50, s45, 1
	s_sub_i32 s49, s48, s44
	s_cmp_ge_u32 s48, s44
	s_cselect_b32 s45, s50, s45
	s_cselect_b32 s48, s49, s48
	s_add_i32 s49, s45, 1
	s_cmp_ge_u32 s48, s44
	s_cselect_b32 s44, s49, s45
	s_xor_b32 s44, s44, s47
	s_sub_i32 s45, s44, s47
	s_mul_i32 s8, s45, s8
	s_add_i32 s12, s12, s18
	s_sub_i32 s12, s12, s8
	s_lshl_b32 s8, s46, 10
	s_lshl_b32 s45, s45, 7
	v_xor_b32_e32 v0, v19, v80
	s_add_i32 s8, s45, s8
	v_or_b32_e32 v1, v18, v17
	v_lshlrev_b32_e32 v0, 3, v0
	v_add_u32_e32 v2, s8, v1
	v_and_b32_e32 v20, 56, v0
	v_or_b32_e32 v3, 8, v1
	v_lshl_or_b32 v192, v2, 10, v20
	v_lshrrev_b32_e32 v2, 1, v3
	s_lshl_b32 s12, s12, 10
	v_readlane_b32 s9, v252, 39
	v_xor_b32_e32 v2, v2, v80
	s_or_b32 s12, s12, s9
	v_lshlrev_b32_e32 v2, 3, v2
	v_add_u32_e32 v4, s8, v3
	v_and_b32_e32 v21, 56, v2
	v_add_u32_e32 v3, s12, v3
	v_lshl_or_b32 v2, v4, 10, v21
	v_lshl_or_b32 v4, v3, 10, v21
	v_or_b32_e32 v3, 16, v1
	v_add_u32_e32 v0, s12, v1
	v_add_u32_e32 v5, s8, v3
	v_add_u32_e32 v3, s12, v3
	v_or_b32_e32 v1, 24, v1
	v_lshl_or_b32 v8, v3, 10, v20
	v_lshrrev_b32_e32 v3, 1, v1
	v_xor_b32_e32 v3, v3, v80
	s_cmp_lg_u32 32, -1
	v_lshlrev_b32_e32 v3, 3, v3
	v_lshlrev_b32_e32 v23, 12, v16
	s_cselect_b32 s45, 32, 0
	v_lshl_or_b32 v6, v5, 10, v20
	v_add_u32_e32 v5, s8, v1
	v_and_b32_e32 v22, 56, v3
	v_add_u32_e32 v1, s12, v1
	v_add_u32_e32 v82, s45, v23
	v_ashrrev_i32_e32 v3, 1, v80
	s_add_i32 s46, s45, 0x4000
	v_lshl_or_b32 v12, v1, 10, v22
	v_and_b32_e32 v1, 15, v80
	v_and_b32_e32 v81, 0xffffffc0, v3
	v_add_u32_e32 v3, s46, v23
	v_readfirstlane_b32 s46, v82
	v_lshl_or_b32 v0, v0, 10, v20
	v_or_b32_e32 v24, v81, v1
	v_lshl_add_u64 v[14:15], v[192:193], 1, s[28:29]
	s_mov_b32 m0, s46
	v_mov_b32_e32 v1, v193
	v_readfirstlane_b32 s46, v3
	global_load_lds_dwordx4 v[14:15], off
	v_lshl_add_u64 v[0:1], v[0:1], 1, s[74:75]
	s_mov_b32 m0, s46
	v_mov_b32_e32 v3, v193
	s_add_i32 s46, s45, 0x400
	global_load_lds_dwordx4 v[0:1], off
	v_lshl_add_u64 v[0:1], v[2:3], 1, s[28:29]
	v_add_u32_e32 v2, s46, v23
	v_lshl_or_b32 v10, v5, 10, v22
	v_readfirstlane_b32 s46, v2
	s_mov_b32 m0, s46
	s_add_i32 s46, s45, 0x4400
	v_add_u32_e32 v2, s46, v23
	global_load_lds_dwordx4 v[0:1], off
	v_readfirstlane_b32 s46, v2
	s_mov_b32 m0, s46
	s_add_i32 s46, s45, 0x800
	v_mov_b32_e32 v5, v193
	v_add_u32_e32 v2, s46, v23
	v_lshl_add_u64 v[0:1], v[4:5], 1, s[74:75]
	v_readfirstlane_b32 s46, v2
	global_load_lds_dwordx4 v[0:1], off
	s_mov_b32 m0, s46
	s_add_i32 s46, s45, 0x4800
	v_mov_b32_e32 v7, v193
	v_add_u32_e32 v2, s46, v23
	v_lshl_add_u64 v[0:1], v[6:7], 1, s[28:29]
	v_readfirstlane_b32 s46, v2
	global_load_lds_dwordx4 v[0:1], off
	s_mov_b32 m0, s46
	s_add_i32 s46, s45, 0xc00
	v_mov_b32_e32 v9, v193
	v_add_u32_e32 v2, s46, v23
	s_addk_i32 s45, 0x4c00
	v_lshl_add_u64 v[0:1], v[8:9], 1, s[74:75]
	v_mov_b32_e32 v11, v193
	v_readfirstlane_b32 s46, v2
	v_add_u32_e32 v2, s45, v23
	global_load_lds_dwordx4 v[0:1], off
	v_lshl_add_u64 v[0:1], v[10:11], 1, s[28:29]
	s_mov_b32 m0, s46
	v_mov_b32_e32 v13, v193
	v_readfirstlane_b32 s45, v2
	global_load_lds_dwordx4 v[0:1], off
	v_lshl_add_u64 v[0:1], v[12:13], 1, s[74:75]
	s_mov_b32 m0, s45
	s_lshl_b32 s45, s43, 10
	global_load_lds_dwordx4 v[0:1], off
	v_bfe_u32 v0, v80, 1, 3
	s_lshl_b32 s46, s44, 7
	v_xor_b32_e32 v1, v19, v0
	v_bitop3_b32 v0, v19, v0, 4 bitop3:0x36
	s_add_i32 s46, s46, s45
	v_lshlrev_b32_e32 v83, 4, v0
	v_or_b32_e32 v0, s46, v17
	v_add_u32_e32 v0, v0, v18
	s_lshl_b32 s45, s47, 7
	v_subrev_u32_e32 v0, s45, v0
	s_lshl_b32 s45, s42, 10
	v_subrev_u32_e32 v0, s45, v0
	s_lshl_b32 s45, s43, 20
	s_lshl_b32 s46, s44, 17
	v_lshl_or_b32 v192, v0, 10, v20
	v_lshlrev_b32_e32 v0, 15, v16
	s_add_i32 s45, s45, s46
	v_lshlrev_b32_e32 v84, 4, v1
	v_lshlrev_b32_e32 v1, 10, v17
	v_add_u32_e32 v2, s45, v0
	v_or_b32_e32 v2, v2, v1
	s_add_i32 s18, s19, s18
	s_lshl_b32 s19, s42, 3
	v_or3_b32 v3, v2, v21, s33
	s_lshl_b32 s45, s47, 17
	s_add_i32 s47, s47, s19
	v_subrev_u32_e32 v3, s45, v3
	s_lshl_b32 s46, s42, 20
	s_sub_i32 s19, s47, s44
	s_lshl_b32 s42, s43, 3
	v_lshl_add_u64 v[64:65], v[192:193], 1, s[40:41]
	v_subrev_u32_e32 v192, s46, v3
	v_or3_b32 v3, v2, v20, s68
	s_sub_i32 s19, s19, s42
	s_min_i32 s17, s17, 8
	v_subrev_u32_e32 v3, s45, v3
	v_or3_b32 v2, v2, v22, s67
	s_mul_i32 s19, s19, s17
	v_lshl_add_u64 v[66:67], v[192:193], 1, s[40:41]
	v_subrev_u32_e32 v192, s46, v3
	v_subrev_u32_e32 v2, s45, v2
	s_add_i32 s18, s18, s19
	v_lshl_add_u64 v[68:69], v[192:193], 1, s[40:41]
	v_subrev_u32_e32 v192, s46, v2
	v_add_u32_e32 v2, s31, v17
	s_lshl_b32 s17, s18, 10
	v_add3_u32 v2, v2, v18, s17
	v_lshl_add_u64 v[70:71], v[192:193], 1, s[40:41]
	v_lshl_or_b32 v192, v2, 10, v20
	v_add3_u32 v2, s58, v0, v1
	s_lshl_b32 s17, s18, 20
	v_lshl_add_u64 v[72:73], v[192:193], 1, s[56:57]
	v_add3_u32 v192, v2, v21, s17
	v_add3_u32 v2, s59, v0, v1
	v_readlane_b32 s9, v254, 34
	s_waitcnt vmcnt(0)
	v_lshl_add_u64 v[74:75], v[192:193], 1, s[56:57]
	v_add3_u32 v192, v2, v20, s17
	v_add3_u32 v0, s9, v0, v1
	v_lshlrev_b32_e32 v25, 7, v80
	v_lshl_add_u64 v[76:77], v[192:193], 1, s[56:57]
	v_add3_u32 v192, v0, v22, s17
	v_mov_b32_e32 v0, 0
	s_mov_b32 s16, 0
	v_lshlrev_b32_e32 v85, 7, v24
	v_and_b32_e32 v86, 0x2780, v25
	v_lshl_add_u64 v[78:79], v[192:193], 1, s[56:57]
	s_mov_b64 s[42:43], 0
	v_mov_b32_e32 v1, v0
	v_mov_b32_e32 v2, v0
	v_mov_b32_e32 v3, v0
	v_mov_b32_e32 v4, v0
	v_mov_b32_e32 v5, v0
	v_mov_b32_e32 v6, v0
	v_mov_b32_e32 v7, v0
	v_mov_b32_e32 v8, v0
	v_mov_b32_e32 v9, v0
	v_mov_b32_e32 v10, v0
	v_mov_b32_e32 v11, v0
	v_mov_b32_e32 v12, v0
	v_mov_b32_e32 v13, v0
	v_mov_b32_e32 v14, v0
	v_mov_b32_e32 v15, v0
	v_mov_b32_e32 v16, v0
	v_mov_b32_e32 v17, v0
	v_mov_b32_e32 v18, v0
	v_mov_b32_e32 v19, v0
	v_mov_b32_e32 v20, v0
	v_mov_b32_e32 v21, v0
	v_mov_b32_e32 v22, v0
	v_mov_b32_e32 v23, v0
	v_mov_b32_e32 v24, v0
	v_mov_b32_e32 v25, v0
	v_mov_b32_e32 v26, v0
	v_mov_b32_e32 v27, v0
	v_mov_b32_e32 v28, v0
	v_mov_b32_e32 v29, v0
	v_mov_b32_e32 v30, v0
	v_mov_b32_e32 v31, v0
	v_mov_b32_e32 v32, v0
	v_mov_b32_e32 v33, v0
	v_mov_b32_e32 v34, v0
	v_mov_b32_e32 v35, v0
	v_mov_b32_e32 v36, v0
	v_mov_b32_e32 v37, v0
	v_mov_b32_e32 v38, v0
	v_mov_b32_e32 v39, v0
	v_mov_b32_e32 v40, v0
	v_mov_b32_e32 v41, v0
	v_mov_b32_e32 v42, v0
	v_mov_b32_e32 v43, v0
	v_mov_b32_e32 v44, v0
	v_mov_b32_e32 v45, v0
	v_mov_b32_e32 v46, v0
	v_mov_b32_e32 v47, v0
	v_mov_b32_e32 v48, v0
	v_mov_b32_e32 v49, v0
	v_mov_b32_e32 v50, v0
	v_mov_b32_e32 v51, v0
	v_mov_b32_e32 v52, v0
	v_mov_b32_e32 v53, v0
	v_mov_b32_e32 v54, v0
	v_mov_b32_e32 v55, v0
	v_mov_b32_e32 v56, v0
	v_mov_b32_e32 v57, v0
	v_mov_b32_e32 v58, v0
	v_mov_b32_e32 v59, v0
	v_mov_b32_e32 v60, v0
	v_mov_b32_e32 v61, v0
	v_mov_b32_e32 v62, v0
	v_mov_b32_e32 v63, v0
	s_waitcnt vmcnt(0) lgkmcnt(0)
	s_barrier
	v_add_u32_e32 v134, 32, v85
	v_add_u32_e32 v135, 32, v86
	v_add_u32_e32 v132, v134, v84
	v_add_u32_e32 v133, v135, v84
	ds_read_b128 v[88:91], v132
	ds_read_b128 v[96:99], v132 offset:2048
	ds_read_b128 v[104:107], v132 offset:4096
	ds_read_b128 v[112:115], v132 offset:6144
	ds_read_b128 v[92:95], v133 offset:16384
	ds_read_b128 v[100:103], v133 offset:18432
	ds_read_b128 v[108:111], v133 offset:20480
	ds_read_b128 v[116:119], v133 offset:22528
	v_readfirstlane_b32 s98, v64
	v_readfirstlane_b32 s99, v65
	v_readfirstlane_b32 s100, v72
	v_readfirstlane_b32 s101, v73
	s_sub_u32 s98, s98, 0x80
	s_subb_u32 s99, s99, 0
	s_sub_u32 s100, s100, 0x80
	s_subb_u32 s101, s101, 0
	v_subrev_u32_e32 v64, s98, v64
	v_subrev_u32_e32 v66, s98, v66
	v_subrev_u32_e32 v68, s98, v68
	v_subrev_u32_e32 v70, s98, v70
	v_subrev_u32_e32 v72, s100, v72
	v_subrev_u32_e32 v74, s100, v74
	v_subrev_u32_e32 v76, s100, v76
	v_subrev_u32_e32 v78, s100, v78
	v_add_u32_e32 v128, 0x8000, v82
	s_nop 0
	v_readfirstlane_b32 s18, v128
	s_nop 1
	s_mov_b32 m0, s18
	s_nop 0
	global_load_lds_dwordx4 v64, s[98:99]
	s_add_i32 m0, s18, 0x4000
	s_nop 0
	global_load_lds_dwordx4 v72, s[100:101]
	s_add_i32 m0, s18, 0x400
	s_nop 0
	global_load_lds_dwordx4 v66, s[98:99]
	s_add_i32 m0, s18, 0x4400
	s_nop 0
	global_load_lds_dwordx4 v74, s[100:101]
	s_add_i32 m0, s18, 0x800
	s_nop 0
	global_load_lds_dwordx4 v68, s[98:99]
	s_add_i32 m0, s18, 0x4800
	s_nop 0
	global_load_lds_dwordx4 v76, s[100:101]
	s_add_i32 m0, s18, 0xc00
	s_nop 0
	global_load_lds_dwordx4 v70, s[98:99]
	s_add_i32 m0, s18, 0x4c00
	s_nop 0
	global_load_lds_dwordx4 v78, s[100:101]
	s_add_u32 s42, s42, 0x80
	s_addc_u32 s43, s43, 0
	s_add_u32 s98, s98, 0x80
	s_addc_u32 s99, s99, 0
	s_add_u32 s100, s100, 0x80
	s_addc_u32 s101, s101, 0
	.p2align 6

.LBB0_79:
	s_nop 1
	v_sub_co_u32_e64 v0, s[10:11], s2, 64
	s_and_b64 s[10:11], s[10:11], exec
	v_readfirstlane_b32 s3, v0
	v_mov_b32_e32 v80, v220
	s_cselect_b32 s3, s2, s3
	s_cselect_b32 s10, 0, 8
	v_ashrrev_i32_e32 v16, 6, v80
	v_bfe_u32 v19, v80, 4, 2
	s_bfe_u32 s12, s3, 0x50003
	v_bfe_u32 v17, v80, 3, 3
	v_lshlrev_b32_e32 v18, 5, v16
	v_xor_b32_e32 v0, v19, v80
	s_add_i32 s16, s3, s10
	s_lshl_b32 s3, s12, 7
	v_or_b32_e32 v1, v18, v17
	v_lshlrev_b32_e32 v0, 3, v0
	v_add_u32_e32 v2, s3, v1
	v_and_b32_e32 v20, 56, v0
	v_or_b32_e32 v3, 8, v1
	s_lshl_b32 s17, s12, 13
	s_lshl_b32 s18, s16, 10
	v_lshl_or_b32 v192, v2, 10, v20
	v_lshrrev_b32_e32 v2, 1, v3
	s_sub_i32 s10, s18, s17
	v_xor_b32_e32 v2, v2, v80
	s_or_b32 s10, s10, s31
	v_lshlrev_b32_e32 v2, 3, v2
	v_add_u32_e32 v4, s3, v3
	v_and_b32_e32 v21, 56, v2
	v_add_u32_e32 v3, s10, v3
	v_lshl_or_b32 v2, v4, 10, v21
	v_lshl_or_b32 v4, v3, 10, v21
	v_or_b32_e32 v3, 16, v1
	v_add_u32_e32 v0, s10, v1
	v_add_u32_e32 v5, s3, v3
	v_add_u32_e32 v3, s10, v3
	v_or_b32_e32 v1, 24, v1
	v_lshl_or_b32 v8, v3, 10, v20
	v_lshrrev_b32_e32 v3, 1, v1
	v_xor_b32_e32 v3, v3, v80
	v_lshlrev_b32_e32 v3, 3, v3
	s_cmp_lg_u32 32, -1
	v_lshl_or_b32 v6, v5, 10, v20
	v_add_u32_e32 v5, s3, v1
	v_and_b32_e32 v22, 56, v3
	v_add_u32_e32 v1, s10, v1
	v_lshlrev_b32_e32 v23, 12, v16
	s_cselect_b32 s19, 32, 0
	v_ashrrev_i32_e32 v3, 1, v80
	v_lshl_or_b32 v12, v1, 10, v22
	v_add_u32_e32 v82, s19, v23
	v_and_b32_e32 v1, 15, v80
	v_and_b32_e32 v81, 0xffffffc0, v3
	s_add_i32 s40, s19, 0x4000
	v_or_b32_e32 v24, v81, v1
	v_lshlrev_b32_e32 v1, 7, v80
	v_add_u32_e32 v3, s40, v23
	v_readfirstlane_b32 s40, v82
	v_lshl_or_b32 v0, v0, 10, v20
	v_and_b32_e32 v83, 0x2780, v1
	v_lshl_add_u64 v[14:15], v[192:193], 1, s[0:1]
	s_mov_b32 m0, s40
	v_mov_b32_e32 v1, v193
	v_readfirstlane_b32 s40, v3
	global_load_lds_dwordx4 v[14:15], off
	v_lshl_add_u64 v[0:1], v[0:1], 1, s[74:75]
	s_mov_b32 m0, s40
	v_mov_b32_e32 v3, v193
	s_add_i32 s40, s19, 0x400
	global_load_lds_dwordx4 v[0:1], off
	v_lshl_add_u64 v[0:1], v[2:3], 1, s[0:1]
	v_add_u32_e32 v2, s40, v23
	v_lshl_or_b32 v10, v5, 10, v22
	v_readfirstlane_b32 s40, v2
	s_mov_b32 m0, s40
	s_add_i32 s40, s19, 0x4400
	v_add_u32_e32 v2, s40, v23
	global_load_lds_dwordx4 v[0:1], off
	v_readfirstlane_b32 s40, v2
	s_mov_b32 m0, s40
	s_add_i32 s40, s19, 0x800
	v_mov_b32_e32 v5, v193
	v_add_u32_e32 v2, s40, v23
	v_lshl_add_u64 v[0:1], v[4:5], 1, s[74:75]
	v_readfirstlane_b32 s40, v2
	global_load_lds_dwordx4 v[0:1], off
	s_mov_b32 m0, s40
	s_add_i32 s40, s19, 0x4800
	v_mov_b32_e32 v7, v193
	v_add_u32_e32 v2, s40, v23
	v_lshl_add_u64 v[0:1], v[6:7], 1, s[0:1]
	v_readfirstlane_b32 s40, v2
	global_load_lds_dwordx4 v[0:1], off
	s_mov_b32 m0, s40
	s_add_i32 s40, s19, 0xc00
	v_mov_b32_e32 v9, v193
	v_add_u32_e32 v2, s40, v23
	s_addk_i32 s19, 0x4c00
	v_lshl_add_u64 v[0:1], v[8:9], 1, s[74:75]
	v_mov_b32_e32 v11, v193
	v_readfirstlane_b32 s40, v2
	v_add_u32_e32 v2, s19, v23
	global_load_lds_dwordx4 v[0:1], off
	v_lshl_add_u64 v[0:1], v[10:11], 1, s[0:1]
	s_mov_b32 m0, s40
	v_mov_b32_e32 v13, v193
	v_readfirstlane_b32 s19, v2
	global_load_lds_dwordx4 v[0:1], off
	v_lshl_add_u64 v[0:1], v[12:13], 1, s[74:75]
	s_mov_b32 m0, s19
	s_or_b32 s18, s18, s31
	global_load_lds_dwordx4 v[0:1], off
	v_bfe_u32 v0, v80, 1, 3
	v_xor_b32_e32 v1, v19, v0
	v_bitop3_b32 v0, v19, v0, 4 bitop3:0x36
	v_lshlrev_b32_e32 v84, 4, v0
	v_or_b32_e32 v0, s3, v17
	v_add_u32_e32 v0, v0, v18
	v_lshl_or_b32 v192, v0, 10, v20
	v_lshlrev_b32_e32 v0, 15, v16
	v_lshlrev_b32_e32 v86, 4, v1
	v_lshlrev_b32_e32 v1, 10, v17
	v_lshl_add_u32 v2, s12, 17, v0
	v_or_b32_e32 v2, v2, v1
	v_lshl_add_u64 v[64:65], v[192:193], 1, s[28:29]
	v_or3_b32 v192, v2, v21, s33
	v_lshl_add_u64 v[66:67], v[192:193], 1, s[28:29]
	v_or3_b32 v192, v2, v20, s68
	v_lshl_add_u64 v[68:69], v[192:193], 1, s[28:29]
	v_or3_b32 v192, v2, v22, s67
	v_add3_u32 v2, s18, v17, v18
	s_lshl_b32 s16, s16, 20
	v_subrev_u32_e32 v2, s17, v2
	s_or_b32 s17, s58, s16
	v_lshl_add_u64 v[70:71], v[192:193], 1, s[28:29]
	v_lshl_or_b32 v192, v2, 10, v20
	v_add_u32_e32 v2, s17, v0
	v_add3_u32 v2, v2, v1, v21
	s_lshl_b32 s12, s12, 23
	s_or_b32 s17, s59, s16
	v_readlane_b32 s9, v254, 34
	v_lshl_add_u64 v[72:73], v[192:193], 1, s[56:57]
	v_subrev_u32_e32 v192, s12, v2
	v_add_u32_e32 v2, s17, v0
	s_or_b32 s16, s9, s16
	v_add3_u32 v2, v2, v1, v20
	v_add_u32_e32 v0, s16, v0
	s_waitcnt vmcnt(0)
	v_lshl_add_u64 v[74:75], v[192:193], 1, s[56:57]
	v_subrev_u32_e32 v192, s12, v2
	v_add3_u32 v0, v0, v1, v22
	v_lshl_add_u64 v[76:77], v[192:193], 1, s[56:57]
	v_subrev_u32_e32 v192, s12, v0
	v_mov_b32_e32 v0, 0
	s_mov_b32 s11, 0
	v_lshlrev_b32_e32 v85, 7, v24
	v_lshl_add_u64 v[78:79], v[192:193], 1, s[56:57]
	s_mov_b64 s[40:41], 0
	v_mov_b32_e32 v1, v0
	v_mov_b32_e32 v2, v0
	v_mov_b32_e32 v3, v0
	v_mov_b32_e32 v4, v0
	v_mov_b32_e32 v5, v0
	v_mov_b32_e32 v6, v0
	v_mov_b32_e32 v7, v0
	v_mov_b32_e32 v8, v0
	v_mov_b32_e32 v9, v0
	v_mov_b32_e32 v10, v0
	v_mov_b32_e32 v11, v0
	v_mov_b32_e32 v12, v0
	v_mov_b32_e32 v13, v0
	v_mov_b32_e32 v14, v0
	v_mov_b32_e32 v15, v0
	v_mov_b32_e32 v16, v0
	v_mov_b32_e32 v17, v0
	v_mov_b32_e32 v18, v0
	v_mov_b32_e32 v19, v0
	v_mov_b32_e32 v20, v0
	v_mov_b32_e32 v21, v0
	v_mov_b32_e32 v22, v0
	v_mov_b32_e32 v23, v0
	v_mov_b32_e32 v24, v0
	v_mov_b32_e32 v25, v0
	v_mov_b32_e32 v26, v0
	v_mov_b32_e32 v27, v0
	v_mov_b32_e32 v28, v0
	v_mov_b32_e32 v29, v0
	v_mov_b32_e32 v30, v0
	v_mov_b32_e32 v31, v0
	v_mov_b32_e32 v32, v0
	v_mov_b32_e32 v33, v0
	v_mov_b32_e32 v34, v0
	v_mov_b32_e32 v35, v0
	v_mov_b32_e32 v36, v0
	v_mov_b32_e32 v37, v0
	v_mov_b32_e32 v38, v0
	v_mov_b32_e32 v39, v0
	v_mov_b32_e32 v40, v0
	v_mov_b32_e32 v41, v0
	v_mov_b32_e32 v42, v0
	v_mov_b32_e32 v43, v0
	v_mov_b32_e32 v44, v0
	v_mov_b32_e32 v45, v0
	v_mov_b32_e32 v46, v0
	v_mov_b32_e32 v47, v0
	v_mov_b32_e32 v48, v0
	v_mov_b32_e32 v49, v0
	v_mov_b32_e32 v50, v0
	v_mov_b32_e32 v51, v0
	v_mov_b32_e32 v52, v0
	v_mov_b32_e32 v53, v0
	v_mov_b32_e32 v54, v0
	v_mov_b32_e32 v55, v0
	v_mov_b32_e32 v56, v0
	v_mov_b32_e32 v57, v0
	v_mov_b32_e32 v58, v0
	v_mov_b32_e32 v59, v0
	v_mov_b32_e32 v60, v0
	v_mov_b32_e32 v61, v0
	v_mov_b32_e32 v62, v0
	v_mov_b32_e32 v63, v0
	s_waitcnt vmcnt(0) lgkmcnt(0)
	s_barrier
	v_add_u32_e32 v134, 32, v85
	v_add_u32_e32 v135, 32, v83
	v_add_u32_e32 v132, v134, v86
	v_add_u32_e32 v133, v135, v86
	ds_read_b128 v[88:91], v132
	ds_read_b128 v[96:99], v132 offset:2048
	ds_read_b128 v[104:107], v132 offset:4096
	ds_read_b128 v[112:115], v132 offset:6144
	ds_read_b128 v[92:95], v133 offset:16384
	ds_read_b128 v[100:103], v133 offset:18432
	ds_read_b128 v[108:111], v133 offset:20480
	ds_read_b128 v[116:119], v133 offset:22528
	v_readfirstlane_b32 s98, v64
	v_readfirstlane_b32 s99, v65
	v_readfirstlane_b32 s100, v72
	v_readfirstlane_b32 s101, v73
	s_sub_u32 s98, s98, 0x80
	s_subb_u32 s99, s99, 0
	s_sub_u32 s100, s100, 0x80
	s_subb_u32 s101, s101, 0
	v_subrev_u32_e32 v64, s98, v64
	v_subrev_u32_e32 v66, s98, v66
	v_subrev_u32_e32 v68, s98, v68
	v_subrev_u32_e32 v70, s98, v70
	v_subrev_u32_e32 v72, s100, v72
	v_subrev_u32_e32 v74, s100, v74
	v_subrev_u32_e32 v76, s100, v76
	v_subrev_u32_e32 v78, s100, v78
	v_add_u32_e32 v128, 0x8000, v82
	s_nop 0
	v_readfirstlane_b32 s16, v128
	s_nop 1
	s_mov_b32 m0, s16
	s_nop 0
	global_load_lds_dwordx4 v64, s[98:99]
	s_add_i32 m0, s16, 0x4000
	s_nop 0
	global_load_lds_dwordx4 v72, s[100:101]
	s_add_i32 m0, s16, 0x400
	s_nop 0
	global_load_lds_dwordx4 v66, s[98:99]
	s_add_i32 m0, s16, 0x4400
	s_nop 0
	global_load_lds_dwordx4 v74, s[100:101]
	s_add_i32 m0, s16, 0x800
	s_nop 0
	global_load_lds_dwordx4 v68, s[98:99]
	s_add_i32 m0, s16, 0x4800
	s_nop 0
	global_load_lds_dwordx4 v76, s[100:101]
	s_add_i32 m0, s16, 0xc00
	s_nop 0
	global_load_lds_dwordx4 v70, s[98:99]
	s_add_i32 m0, s16, 0x4c00
	s_nop 0
	global_load_lds_dwordx4 v78, s[100:101]
	s_add_u32 s40, s40, 0x80
	s_addc_u32 s41, s41, 0
	s_add_u32 s98, s98, 0x80
	s_addc_u32 s99, s99, 0
	s_add_u32 s100, s100, 0x80
	s_addc_u32 s101, s101, 0
	.p2align 6

.LBB0_134:
	v_exp_f32_e32 v228, v96
	v_exp_f32_e32 v112, v112
	v_exp_f32_e32 v96, v113
	v_exp_f32_e32 v113, v97
	v_exp_f32_e32 v233, v98
	v_exp_f32_e32 v114, v114
	v_exp_f32_e32 v98, v115
	v_add_f32_e32 v229, v113, v228
	v_exp_f32_e32 v115, v99
	v_exp_f32_e32 v116, v116
	v_add_f32_e32 v97, v96, v112
	v_add_f32_e32 v99, v233, v229
	v_exp_f32_e32 v229, v100
	v_exp_f32_e32 v100, v117
	v_add_f32_e32 v97, v114, v97
	v_exp_f32_e32 v117, v101
	v_exp_f32_e32 v101, v118
	v_add_f32_e32 v97, v98, v97
	v_exp_f32_e32 v118, v102
	v_exp_f32_e32 v102, v119
	v_add_f32_e32 v99, v115, v99
	v_add_f32_e32 v97, v116, v97
	v_exp_f32_e32 v103, v103
	v_exp_f32_e32 v119, v120
	v_add_f32_e32 v99, v229, v99
	v_add_f32_e32 v97, v100, v97
	v_exp_f32_e32 v120, v104
	v_exp_f32_e32 v104, v121
	v_add_f32_e32 v99, v117, v99
	v_add_f32_e32 v97, v101, v97
	v_exp_f32_e32 v121, v105
	v_exp_f32_e32 v105, v122
	v_add_f32_e32 v99, v118, v99
	v_add_f32_e32 v97, v102, v97
	v_exp_f32_e32 v122, v106
	v_exp_f32_e32 v106, v123
	v_add_f32_e32 v99, v103, v99
	v_add_f32_e32 v97, v119, v97
	v_exp_f32_e32 v123, v107
	v_exp_f32_e32 v107, v124
	v_add_f32_e32 v99, v120, v99
	v_add_f32_e32 v97, v104, v97
	v_exp_f32_e32 v124, v108
	v_exp_f32_e32 v108, v125
	v_add_f32_e32 v99, v121, v99
	v_add_f32_e32 v97, v105, v97
	v_exp_f32_e32 v125, v109
	v_exp_f32_e32 v109, v126
	v_exp_f32_e32 v126, v110
	v_exp_f32_e32 v110, v127
	v_add_f32_e32 v99, v122, v99
	v_add_f32_e32 v97, v106, v97
	v_add_f32_e32 v99, v123, v99
	v_add_f32_e32 v97, v107, v97
	v_exp_f32_e32 v111, v111
	v_add_f32_e32 v99, v124, v99
	v_add_f32_e32 v97, v108, v97
	v_cvt_pk_bf16_f32 v105, v105, v106
	v_cvt_pk_bf16_f32 v106, v107, v108
	v_cvt_pk_bf16_f32 v108, v120, v121
	v_exp_f32_e32 v120, v80
	v_exp_f32_e32 v121, v64
	v_add_f32_e32 v99, v125, v99
	v_add_f32_e32 v97, v109, v97
	v_cvt_pk_bf16_f32 v107, v109, v110
	v_cvt_pk_bf16_f32 v109, v122, v123
	v_exp_f32_e32 v122, v81
	v_exp_f32_e32 v123, v65
	v_add_f32_e32 v99, v126, v99
	v_add_f32_e32 v97, v110, v97
	v_cvt_pk_bf16_f32 v110, v124, v125
	v_exp_f32_e32 v124, v82
	v_exp_f32_e32 v125, v66
	v_add_f32_e32 v99, v111, v99
	v_cvt_pk_bf16_f32 v111, v126, v111
	v_exp_f32_e32 v66, v83
	v_exp_f32_e32 v126, v67
	v_exp_f32_e32 v81, v84
	v_exp_f32_e32 v80, v68
	v_add_f32_e32 v64, v122, v120
	v_add_f32_e32 v65, v123, v121
	v_exp_f32_e32 v83, v85
	v_exp_f32_e32 v82, v69
	v_add_f32_e32 v64, v124, v64
	v_add_f32_e32 v67, v125, v65
	v_exp_f32_e32 v85, v86
	v_exp_f32_e32 v84, v70
	v_add_f32_e32 v97, v99, v97
	v_add_f32_e32 v65, v66, v64
	v_add_f32_e32 v64, v126, v67
	v_exp_f32_e32 v87, v87
	v_exp_f32_e32 v86, v71
	v_add_f32_e32 v222, v222, v97
	v_cvt_pk_bf16_f32 v96, v112, v96
	v_cvt_pk_bf16_f32 v97, v114, v98
	v_cvt_pk_bf16_f32 v98, v116, v100
	v_cvt_pk_bf16_f32 v100, v228, v113
	v_exp_f32_e32 v113, v88
	v_exp_f32_e32 v112, v72
	v_add_f32_e32 v64, v80, v64
	v_add_f32_e32 v65, v81, v65
	v_exp_f32_e32 v89, v89
	v_exp_f32_e32 v88, v73
	v_add_f32_e32 v64, v82, v64
	v_add_f32_e32 v65, v83, v65
	v_cvt_pk_bf16_f32 v99, v101, v102
	v_cvt_pk_bf16_f32 v101, v233, v115
	v_exp_f32_e32 v115, v90
	v_exp_f32_e32 v114, v74
	v_add_f32_e32 v64, v84, v64
	v_add_f32_e32 v65, v85, v65
	v_exp_f32_e32 v91, v91
	v_exp_f32_e32 v90, v75
	v_add_f32_e32 v64, v86, v64
	v_add_f32_e32 v65, v87, v65
	v_cvt_pk_bf16_f32 v102, v229, v117
	v_exp_f32_e32 v117, v92
	v_exp_f32_e32 v116, v76
	v_add_f32_e32 v64, v112, v64
	v_add_f32_e32 v65, v113, v65
	v_exp_f32_e32 v93, v93
	v_exp_f32_e32 v92, v77
	v_add_f32_e32 v64, v88, v64
	v_add_f32_e32 v65, v89, v65
	v_cvt_pk_bf16_f32 v103, v118, v103
	v_cvt_pk_bf16_f32 v104, v119, v104
	v_exp_f32_e32 v119, v94
	v_exp_f32_e32 v118, v78
	v_add_f32_e32 v64, v114, v64
	v_add_f32_e32 v65, v115, v65
	v_exp_f32_e32 v95, v95
	v_exp_f32_e32 v94, v79
	v_add_f32_e32 v64, v90, v64
	v_add_f32_e32 v65, v91, v65
	v_cvt_pk_bf16_f32 v67, v85, v87
	v_add_f32_e32 v64, v116, v64
	v_add_f32_e32 v65, v117, v65
	v_cvt_pk_bf16_f32 v68, v121, v123
	v_add_f32_e32 v64, v92, v64
	v_add_f32_e32 v65, v93, v65
	v_cvt_pk_bf16_f32 v69, v125, v126
	v_add_f32_e32 v64, v118, v64
	v_add_f32_e32 v65, v119, v65
	v_cvt_pk_bf16_f32 v70, v80, v82
	v_add_f32_e32 v64, v94, v64
	v_add_f32_e32 v65, v95, v65
	v_cvt_pk_bf16_f32 v71, v84, v86
	v_add_f32_e32 v64, v64, v65
	v_add_f32_e32 v227, v227, v64
	v_cvt_pk_bf16_f32 v64, v120, v122
	v_cvt_pk_bf16_f32 v65, v124, v66
	v_cvt_pk_bf16_f32 v66, v81, v83
	v_cvt_pk_bf16_f32 v72, v113, v89
	v_cvt_pk_bf16_f32 v73, v115, v91
	v_cvt_pk_bf16_f32 v74, v117, v93
	v_cvt_pk_bf16_f32 v75, v119, v95
	v_cvt_pk_bf16_f32 v76, v112, v88
	v_cvt_pk_bf16_f32 v77, v114, v90
	v_cvt_pk_bf16_f32 v78, v116, v92
	v_cvt_pk_bf16_f32 v79, v118, v94
	s_waitcnt lgkmcnt(0)
	v_mfma_f32_32x32x16_bf16 v[48:63], v[188:191], v[96:99], v[48:63]
	s_waitcnt vmcnt(0)
	s_add_i32 s2, s13, s10
	s_addk_i32 s45, 0x4000
	s_cmpk_lg_i32 s2, 0x83
	s_waitcnt vmcnt(0)
	s_barrier
	v_mfma_f32_32x32x16_bf16 v[32:47], v[184:187], v[96:99], v[32:47]
	v_mfma_f32_32x32x16_bf16 v[16:31], v[188:191], v[64:67], v[16:31]
	v_mfma_f32_32x32x16_bf16 v[0:15], v[184:187], v[64:67], v[0:15]
	v_mfma_f32_32x32x16_bf16 v[48:63], v[180:183], v[104:107], v[48:63]
	v_mfma_f32_32x32x16_bf16 v[32:47], v[176:179], v[104:107], v[32:47]
	v_mfma_f32_32x32x16_bf16 v[16:31], v[180:183], v[72:75], v[16:31]
	v_mfma_f32_32x32x16_bf16 v[0:15], v[176:179], v[72:75], v[0:15]
	v_mfma_f32_32x32x16_bf16 v[48:63], v[172:175], v[100:103], v[48:63]
	v_mfma_f32_32x32x16_bf16 v[32:47], v[168:171], v[100:103], v[32:47]
	v_mfma_f32_32x32x16_bf16 v[16:31], v[172:175], v[68:71], v[16:31]
	v_mfma_f32_32x32x16_bf16 v[0:15], v[168:171], v[68:71], v[0:15]
	v_mfma_f32_32x32x16_bf16 v[48:63], v[164:167], v[108:111], v[48:63]
	v_mfma_f32_32x32x16_bf16 v[32:47], v[160:163], v[108:111], v[32:47]
	v_mfma_f32_32x32x16_bf16 v[16:31], v[164:167], v[76:79], v[16:31]
	v_mfma_f32_32x32x16_bf16 v[0:15], v[160:163], v[76:79], v[0:15]
	s_cbranch_scc0 .LBB0_147
	.p2align 6

.LBB0_158:
	v_add_f32_e32 v111, 0, v123
	v_add_f32_e32 v119, 0, v125
	v_add_f32_e32 v111, v126, v111
	v_add_f32_e32 v119, v127, v119
	v_exp_f32_e32 v127, v64
	v_exp_f32_e32 v126, v80
	v_exp_f32_e32 v65, v65
	v_exp_f32_e32 v64, v81
	v_add_f32_e32 v111, v130, v111
	v_add_f32_e32 v119, v131, v119
	v_exp_f32_e32 v131, v66
	v_exp_f32_e32 v130, v82
	v_exp_f32_e32 v67, v67
	v_exp_f32_e32 v66, v83
	v_pk_add_f32 v[80:81], v[126:127], 0 op_sel_hi:[1,0]
	v_exp_f32_e32 v83, v68
	v_exp_f32_e32 v82, v84
	v_add_f32_e32 v111, v132, v111
	v_add_f32_e32 v119, v133, v119
	v_pk_add_f32 v[80:81], v[64:65], v[80:81]
	v_exp_f32_e32 v133, v69
	v_exp_f32_e32 v132, v85
	v_add_f32_e32 v111, v134, v111
	v_pk_add_f32 v[80:81], v[130:131], v[80:81]
	v_exp_f32_e32 v85, v70
	v_exp_f32_e32 v84, v86
	v_add_f32_e32 v119, v135, v119
	v_add_f32_e32 v111, v140, v111
	v_pk_add_f32 v[80:81], v[66:67], v[80:81]
	v_exp_f32_e32 v135, v71
	v_exp_f32_e32 v134, v87
	v_add_f32_e32 v111, v142, v111
	v_exp_f32_e32 v87, v72
	v_exp_f32_e32 v86, v88
	v_pk_add_f32 v[68:69], v[82:83], v[80:81]
	v_add_f32_e32 v119, v141, v119
	v_add_f32_e32 v111, v143, v111
	v_exp_f32_e32 v141, v73
	v_exp_f32_e32 v140, v89
	v_pk_add_f32 v[68:69], v[132:133], v[68:69]
	v_add_f32_e32 v111, v146, v111
	v_exp_f32_e32 v89, v74
	v_exp_f32_e32 v88, v90
	v_pk_add_f32 v[68:69], v[84:85], v[68:69]
	v_add_f32_e32 v111, v145, v111
	v_exp_f32_e32 v143, v75
	v_exp_f32_e32 v142, v91
	v_pk_add_f32 v[68:69], v[134:135], v[68:69]
	v_add_f32_e32 v111, v144, v111
	v_exp_f32_e32 v91, v76
	v_exp_f32_e32 v90, v92
	v_pk_add_f32 v[68:69], v[86:87], v[68:69]
	v_add_f32_e32 v111, v149, v111
	v_exp_f32_e32 v145, v77
	v_exp_f32_e32 v144, v93
	v_pk_add_f32 v[68:69], v[140:141], v[68:69]
	v_add_f32_e32 v111, v148, v111
	v_exp_f32_e32 v93, v78
	v_exp_f32_e32 v92, v94
	v_pk_add_f32 v[68:69], v[88:89], v[68:69]
	v_add_f32_e32 v111, v147, v111
	v_exp_f32_e32 v147, v79
	v_exp_f32_e32 v146, v95
	v_pk_add_f32 v[68:69], v[142:143], v[68:69]
	v_cvt_pk_bf16_f32 v76, v127, v65
	v_pk_add_f32 v[68:69], v[90:91], v[68:69]
	v_cvt_pk_bf16_f32 v78, v83, v133
	v_pk_add_f32 v[68:69], v[144:145], v[68:69]
	v_cvt_pk_bf16_f32 v79, v85, v135
	v_pk_add_f32 v[68:69], v[92:93], v[68:69]
	v_cvt_pk_bf16_f32 v70, v82, v132
	v_pk_add_f32 v[68:69], v[146:147], v[68:69]
	v_cvt_pk_bf16_f32 v71, v84, v134
	v_add_f32_e32 v80, v68, v69
	v_cvt_pk_bf16_f32 v68, v126, v64
	v_cvt_pk_bf16_f32 v72, v87, v141
	v_cvt_pk_bf16_f32 v73, v89, v143
	v_cvt_pk_bf16_f32 v64, v86, v140
	v_cvt_pk_bf16_f32 v65, v88, v142
	ds_read_b128 v[82:85], v122 offset:16384
	ds_read_b128 v[86:89], v122 offset:20480
	v_cvt_pk_bf16_f32 v77, v131, v67
	v_cvt_pk_bf16_f32 v74, v91, v145
	v_cvt_pk_bf16_f32 v75, v93, v147
	s_waitcnt lgkmcnt(0)
	v_mfma_f32_32x32x16_bf16 v[0:15], v[82:85], v[76:79], v[0:15]
	ds_read_b128 v[82:85], v121 offset:20480
	v_cvt_pk_bf16_f32 v69, v130, v66
	v_add_f32_e32 v119, v154, v119
	v_add_f32_e32 v119, v153, v119
	v_add_f32_e32 v119, v152, v119
	v_add_f32_e32 v119, v156, v119
	v_add_f32_e32 v119, v155, v119
	v_mfma_f32_32x32x16_bf16 v[16:31], v[86:89], v[76:79], v[16:31]
	ds_read_b128 v[76:79], v121 offset:16384
	v_cvt_pk_bf16_f32 v66, v90, v144
	v_cvt_pk_bf16_f32 v67, v92, v146
	v_add_f32_e32 v119, v159, v119
	v_add_f32_e32 v119, v158, v119
	v_add_f32_e32 v119, v157, v119
	v_add_f32_e32 v111, v151, v111
	s_waitcnt lgkmcnt(0)
	v_mfma_f32_32x32x16_bf16 v[0:15], v[76:79], v[72:75], v[0:15]
	ds_read_b128 v[76:79], v120 offset:20480
	v_add_f32_e32 v119, v161, v119
	v_add_f32_e32 v111, v150, v111
	v_add_f32_e32 v119, v160, v119
	v_add_f32_e32 v111, v119, v111
	s_sub_i32 s11, 0x82, s13
	v_add_f32_e32 v111, 0, v111
	v_mfma_f32_32x32x16_bf16 v[16:31], v[82:85], v[72:75], v[16:31]
	ds_read_b128 v[72:75], v120 offset:16384
	s_cmp_lt_u32 s12, 64
	v_add_f32_e32 v175, v111, v80
	s_cselect_b64 s[42:43], -1, 0
	s_cmp_gt_u32 s12, 63
	s_waitcnt lgkmcnt(0)
	v_mfma_f32_32x32x16_bf16 v[0:15], v[72:75], v[68:71], v[0:15]
	ds_read_b128 v[72:75], v110 offset:20480
	v_mfma_f32_32x32x16_bf16 v[16:31], v[76:79], v[68:71], v[16:31]
	ds_read_b128 v[68:71], v110 offset:16384
	s_waitcnt vmcnt(0)
	s_waitcnt vmcnt(0) lgkmcnt(0)
	s_barrier
	v_mfma_f32_32x32x16_bf16 v[0:15], v[68:71], v[64:67], v[0:15]
	v_mfma_f32_32x32x16_bf16 v[16:31], v[72:75], v[64:67], v[16:31]
	s_cbranch_scc1 .LBB0_173
	v_add_u32_e32 v241, v115, v116
	v_add_u32_e32 v242, v115, v117
	v_add_u32_e32 v243, v118, v114
	v_add_u32_e32 v244, v118, v124
	v_add_u32_e32 v245, v118, v128
	v_add_u32_e32 v246, v118, v129
	s_mov_b64 s[100:101], s[50:51]
	v_readfirstlane_b32 s98, v109
	v_readfirstlane_b32 s99, v113
	v_lshlrev_b32_e32 v222, 1, v192
	v_lshlrev_b32_e32 v227, 1, v104
	v_lshlrev_b32_e32 v228, 1, v106
	v_lshl_add_u64 v[110:111], v[192:193], 1, s[50:51]
	s_mov_b32 s50, 2
	s_movk_i32 s12, 0x3000
	s_mov_b32 s10, 0
	s_movk_i32 s2, 0x6000
	.p2align 6

.LBB0_189:
	v_add_f32_e32 v152, 0, v152
	v_add_f32_e32 v153, 0, v153
	v_add_f32_e32 v152, v154, v152
	v_add_f32_e32 v153, v155, v153
	v_exp_f32_e32 v155, v96
	v_exp_f32_e32 v154, v112
	v_exp_f32_e32 v97, v97
	v_exp_f32_e32 v96, v113
	v_add_f32_e32 v152, v156, v152
	v_add_f32_e32 v153, v157, v153
	v_exp_f32_e32 v157, v98
	v_exp_f32_e32 v156, v114
	v_exp_f32_e32 v99, v99
	v_exp_f32_e32 v98, v115
	v_pk_add_f32 v[112:113], v[154:155], 0 op_sel_hi:[1,0]
	v_exp_f32_e32 v115, v100
	v_exp_f32_e32 v114, v116
	v_add_f32_e32 v152, v158, v152
	v_add_f32_e32 v153, v159, v153
	v_pk_add_f32 v[112:113], v[96:97], v[112:113]
	v_exp_f32_e32 v159, v101
	v_exp_f32_e32 v158, v117
	v_pk_add_f32 v[112:113], v[156:157], v[112:113]
	v_exp_f32_e32 v117, v102
	v_exp_f32_e32 v116, v118
	v_add_f32_e32 v152, v160, v152
	v_add_f32_e32 v153, v161, v153
	v_pk_add_f32 v[112:113], v[98:99], v[112:113]
	v_exp_f32_e32 v161, v103
	v_exp_f32_e32 v160, v119
	v_exp_f32_e32 v119, v104
	v_exp_f32_e32 v118, v120
	v_pk_add_f32 v[100:101], v[114:115], v[112:113]
	v_add_f32_e32 v152, v162, v152
	v_add_f32_e32 v153, v163, v153
	v_exp_f32_e32 v163, v105
	v_exp_f32_e32 v162, v121
	v_pk_add_f32 v[100:101], v[158:159], v[100:101]
	v_exp_f32_e32 v121, v106
	v_exp_f32_e32 v120, v122
	v_pk_add_f32 v[100:101], v[116:117], v[100:101]
	v_add_f32_e32 v152, v164, v152
	v_add_f32_e32 v153, v165, v153
	v_exp_f32_e32 v165, v107
	v_exp_f32_e32 v164, v123
	v_pk_add_f32 v[100:101], v[160:161], v[100:101]
	v_exp_f32_e32 v123, v108
	v_exp_f32_e32 v122, v124
	v_pk_add_f32 v[100:101], v[118:119], v[100:101]
	v_add_f32_e32 v152, v166, v152
	v_add_f32_e32 v153, v167, v153
	v_exp_f32_e32 v167, v109
	v_exp_f32_e32 v166, v125
	v_pk_add_f32 v[100:101], v[162:163], v[100:101]
	v_exp_f32_e32 v125, v110
	v_exp_f32_e32 v124, v126
	v_pk_add_f32 v[100:101], v[120:121], v[100:101]
	v_add_f32_e32 v152, v168, v152
	v_add_f32_e32 v153, v169, v153
	v_exp_f32_e32 v169, v111
	v_exp_f32_e32 v168, v127
	v_pk_add_f32 v[100:101], v[164:165], v[100:101]
	v_cvt_pk_bf16_f32 v108, v155, v97
	v_pk_add_f32 v[100:101], v[122:123], v[100:101]
	v_cvt_pk_bf16_f32 v110, v115, v159
	v_pk_add_f32 v[100:101], v[166:167], v[100:101]
	v_cvt_pk_bf16_f32 v111, v117, v161
	v_pk_add_f32 v[100:101], v[124:125], v[100:101]
	v_cvt_pk_bf16_f32 v102, v114, v158
	v_pk_add_f32 v[100:101], v[168:169], v[100:101]
	v_cvt_pk_bf16_f32 v103, v116, v160
	v_add_f32_e32 v112, v100, v101
	v_cvt_pk_bf16_f32 v100, v154, v96
	v_cvt_pk_bf16_f32 v104, v119, v163
	v_cvt_pk_bf16_f32 v105, v121, v165
	v_cvt_pk_bf16_f32 v96, v118, v162
	v_cvt_pk_bf16_f32 v97, v120, v164
	ds_read_b128 v[114:117], v151 offset:16384
	ds_read_b128 v[118:121], v151 offset:20480
	v_cvt_pk_bf16_f32 v109, v157, v99
	v_cvt_pk_bf16_f32 v106, v123, v167
	v_cvt_pk_bf16_f32 v107, v125, v169
	s_waitcnt lgkmcnt(0)
	v_mfma_f32_32x32x16_bf16 v[32:47], v[114:117], v[108:111], v[32:47]
	ds_read_b128 v[114:117], v150 offset:20480
	v_cvt_pk_bf16_f32 v101, v156, v98
	v_add_f32_e32 v152, v175, v152
	v_add_f32_e32 v153, v184, v153
	v_add_f32_e32 v152, v185, v152
	v_add_f32_e32 v153, v186, v153
	v_cvt_pk_bf16_f32 v98, v122, v166
	v_mfma_f32_32x32x16_bf16 v[48:63], v[118:121], v[108:111], v[48:63]
	ds_read_b128 v[108:111], v150 offset:16384
	v_cvt_pk_bf16_f32 v99, v124, v168
	v_add_f32_e32 v152, v187, v152
	v_add_f32_e32 v153, v188, v153
	v_add_f32_e32 v152, v189, v152
	v_add_f32_e32 v153, v190, v153
	v_add_f32_e32 v152, v191, v152
	s_waitcnt lgkmcnt(0)
	v_mfma_f32_32x32x16_bf16 v[32:47], v[108:111], v[104:107], v[32:47]
	ds_read_b128 v[108:111], v147 offset:20480
	v_add_f32_e32 v153, v206, v153
	v_add_f32_e32 v152, v210, v152
	v_add_f32_e32 v153, v212, v153
	v_add_f32_e32 v152, v213, v152
	v_add_f32_e32 v153, v214, v153
	v_add_f32_e32 v152, v153, v152
	v_mfma_f32_32x32x16_bf16 v[48:63], v[114:117], v[104:107], v[48:63]
	ds_read_b128 v[104:107], v147 offset:16384
	v_add_f32_e32 v152, 0, v152
	v_add_f32_e32 v184, v152, v112
	s_andn2_b64 vcc, exec, s[42:43]
	s_waitcnt lgkmcnt(0)
	v_mfma_f32_32x32x16_bf16 v[32:47], v[104:107], v[100:103], v[32:47]
	ds_read_b128 v[104:107], v146 offset:20480
	v_mfma_f32_32x32x16_bf16 v[48:63], v[108:111], v[100:103], v[48:63]
	ds_read_b128 v[100:103], v146 offset:16384
	s_waitcnt vmcnt(0)
	s_waitcnt vmcnt(0) lgkmcnt(0)
	s_barrier
	v_mfma_f32_32x32x16_bf16 v[32:47], v[100:103], v[96:99], v[32:47]
	v_mfma_f32_32x32x16_bf16 v[48:63], v[104:107], v[96:99], v[48:63]
	s_cbranch_vccnz .LBB0_204
	v_add_u32_e32 v241, v172, v173
	v_add_u32_e32 v242, v172, v174
	v_add_u32_e32 v243, v149, v180
	v_add_u32_e32 v244, v149, v181
	v_add_u32_e32 v245, v149, v182
	v_add_u32_e32 v246, v149, v183
	s_mov_b64 s[100:101], s[50:51]
	v_readfirstlane_b32 s98, v170
	v_readfirstlane_b32 s99, v171
	v_lshlrev_b32_e32 v222, 1, v192
	v_lshlrev_b32_e32 v227, 1, v140
	v_lshlrev_b32_e32 v228, 1, v142
	v_lshl_add_u64 v[146:147], v[192:193], 1, s[50:51]
	s_mov_b32 s17, 2
	s_movk_i32 s12, 0x3000
	s_mov_b32 s16, 0
	s_movk_i32 s2, 0x6000
	.p2align 6

.LBB0_221:
	v_exp_f32_e32 v151, v64
	v_exp_f32_e32 v150, v80
	v_exp_f32_e32 v65, v65
	v_exp_f32_e32 v64, v81
	v_add_f32_e32 v142, 0, v158
	v_add_f32_e32 v143, 0, v159
	v_exp_f32_e32 v159, v66
	v_exp_f32_e32 v158, v82
	v_exp_f32_e32 v67, v67
	v_exp_f32_e32 v66, v83
	v_pk_add_f32 v[80:81], v[150:151], 0 op_sel_hi:[1,0]
	v_exp_f32_e32 v83, v68
	v_exp_f32_e32 v82, v84
	v_add_f32_e32 v142, v160, v142
	v_add_f32_e32 v143, v161, v143
	v_pk_add_f32 v[80:81], v[64:65], v[80:81]
	v_exp_f32_e32 v161, v69
	v_exp_f32_e32 v160, v85
	v_pk_add_f32 v[80:81], v[158:159], v[80:81]
	v_exp_f32_e32 v85, v70
	v_exp_f32_e32 v84, v86
	v_add_f32_e32 v142, v162, v142
	v_add_f32_e32 v143, v163, v143
	v_pk_add_f32 v[80:81], v[66:67], v[80:81]
	v_exp_f32_e32 v163, v71
	v_exp_f32_e32 v162, v87
	v_exp_f32_e32 v87, v72
	v_exp_f32_e32 v86, v88
	v_pk_add_f32 v[68:69], v[82:83], v[80:81]
	v_add_f32_e32 v142, v164, v142
	v_add_f32_e32 v143, v165, v143
	v_exp_f32_e32 v165, v73
	v_exp_f32_e32 v164, v89
	v_pk_add_f32 v[68:69], v[160:161], v[68:69]
	v_exp_f32_e32 v89, v74
	v_exp_f32_e32 v88, v90
	v_pk_add_f32 v[68:69], v[84:85], v[68:69]
	v_add_f32_e32 v142, v166, v142
	v_add_f32_e32 v143, v167, v143
	v_exp_f32_e32 v167, v75
	v_exp_f32_e32 v166, v91
	v_pk_add_f32 v[68:69], v[162:163], v[68:69]
	v_exp_f32_e32 v91, v76
	v_exp_f32_e32 v90, v92
	v_pk_add_f32 v[68:69], v[86:87], v[68:69]
	v_add_f32_e32 v142, v168, v142
	v_add_f32_e32 v143, v169, v143
	v_exp_f32_e32 v169, v77
	v_exp_f32_e32 v168, v93
	v_pk_add_f32 v[68:69], v[164:165], v[68:69]
	v_exp_f32_e32 v93, v78
	v_exp_f32_e32 v92, v94
	v_pk_add_f32 v[68:69], v[88:89], v[68:69]
	v_add_f32_e32 v142, v170, v142
	v_add_f32_e32 v143, v171, v143
	v_exp_f32_e32 v171, v79
	v_exp_f32_e32 v170, v95
	v_pk_add_f32 v[68:69], v[166:167], v[68:69]
	v_cvt_pk_bf16_f32 v76, v151, v65
	v_pk_add_f32 v[68:69], v[90:91], v[68:69]
	v_cvt_pk_bf16_f32 v78, v83, v161
	v_pk_add_f32 v[68:69], v[168:169], v[68:69]
	v_cvt_pk_bf16_f32 v79, v85, v163
	v_pk_add_f32 v[68:69], v[92:93], v[68:69]
	v_cvt_pk_bf16_f32 v70, v82, v160
	v_pk_add_f32 v[68:69], v[170:171], v[68:69]
	v_cvt_pk_bf16_f32 v71, v84, v162
	v_add_f32_e32 v80, v68, v69
	v_cvt_pk_bf16_f32 v68, v150, v64
	v_cvt_pk_bf16_f32 v72, v87, v165
	v_cvt_pk_bf16_f32 v73, v89, v167
	v_cvt_pk_bf16_f32 v64, v86, v164
	v_cvt_pk_bf16_f32 v65, v88, v166
	ds_read_b128 v[82:85], v157 offset:32768
	ds_read_b128 v[86:89], v157 offset:36864
	v_cvt_pk_bf16_f32 v77, v159, v67
	v_cvt_pk_bf16_f32 v74, v91, v169
	v_cvt_pk_bf16_f32 v75, v93, v171
	s_waitcnt lgkmcnt(0)
	v_mfma_f32_32x32x16_bf16 v[16:31], v[82:85], v[76:79], v[16:31]
	ds_read_b128 v[82:85], v156 offset:36864
	v_cvt_pk_bf16_f32 v69, v158, v66
	v_add_f32_e32 v142, v172, v142
	v_add_f32_e32 v143, v173, v143
	v_add_f32_e32 v142, v174, v142
	v_add_f32_e32 v143, v175, v143
	v_add_f32_e32 v142, v176, v142
	v_mfma_f32_32x32x16_bf16 v[0:15], v[86:89], v[76:79], v[0:15]
	ds_read_b128 v[76:79], v156 offset:32768
	v_add_f32_e32 v143, v177, v143
	v_add_f32_e32 v142, v178, v142
	v_add_f32_e32 v143, v179, v143
	v_cvt_pk_bf16_f32 v66, v90, v168
	v_cvt_pk_bf16_f32 v67, v92, v170
	v_add_f32_e32 v142, v180, v142
	s_waitcnt lgkmcnt(0)
	v_mfma_f32_32x32x16_bf16 v[16:31], v[76:79], v[72:75], v[16:31]
	ds_read_b128 v[76:79], v155 offset:36864
	v_add_f32_e32 v143, v181, v143
	v_add_f32_e32 v142, v182, v142
	v_add_f32_e32 v143, v183, v143
	v_add_f32_e32 v142, v184, v142
	v_add_f32_e32 v143, v185, v143
	v_add_f32_e32 v142, v186, v142
	v_mfma_f32_32x32x16_bf16 v[0:15], v[82:85], v[72:75], v[0:15]
	ds_read_b128 v[72:75], v155 offset:32768
	v_add_f32_e32 v143, v187, v143
	v_add_f32_e32 v142, v188, v142
	v_add_f32_e32 v143, v189, v143
	v_add_f32_e32 v142, v143, v142
	v_add_f32_e32 v142, 0, v142
	v_add_f32_e32 v149, v142, v80
	s_waitcnt lgkmcnt(0)
	v_mfma_f32_32x32x16_bf16 v[16:31], v[72:75], v[68:71], v[16:31]
	ds_read_b128 v[72:75], v154 offset:36864
	s_cmp_lg_u32 s13, 0
	v_mfma_f32_32x32x16_bf16 v[0:15], v[76:79], v[68:71], v[0:15]
	ds_read_b128 v[68:71], v154 offset:32768
	s_waitcnt vmcnt(0)
	s_waitcnt vmcnt(0) lgkmcnt(0)
	s_barrier
	v_mfma_f32_32x32x16_bf16 v[16:31], v[68:71], v[64:67], v[16:31]
	v_mfma_f32_32x32x16_bf16 v[0:15], v[72:75], v[64:67], v[0:15]
	s_cbranch_scc1 .LBB0_236
	v_readfirstlane_b32 s98, v129
	v_readfirstlane_b32 s99, v130
	v_lshlrev_b32_e32 v206, 1, v192
	v_lshlrev_b32_e32 v210, 1, v120
	v_lshlrev_b32_e32 v222, 1, v122
	v_lshlrev_b32_e32 v227, 1, v124
	v_lshlrev_b32_e32 v228, 1, v126
	s_sub_i32 s10, 0x82, s13
	s_mov_b32 s19, 2
	s_movk_i32 s17, 0x5000
	s_mov_b32 s13, 0
	s_mov_b32 s2, 0xa000
	.p2align 6

.LBB0_253:
	s_min_i32 s2, s3, 8
	s_lshl_b32 s12, s2, 4
	s_mov_b32 s10, s8
	s_add_i32 s1, s1, 8
	s_add_i32 s3, s3, -8
	s_add_i32 s0, s0, -8
	s_sub_i32 s8, s8, s12
	s_cmp_ge_i32 s10, s12
	s_cbranch_scc1 .LBB0_253
	s_lshl_b32 s3, s2, 3
	s_abs_i32 s8, s3
	v_cvt_f32_u32_e32 v0, s8
	s_sub_i32 s16, 0, s8
	s_abs_i32 s13, s10
	s_xor_b32 s12, s10, s3
	v_rcp_iflag_f32_e32 v0, v0
	s_ashr_i32 s12, s12, 31
	v_mov_b32_e32 v81, v220
	v_mul_f32_e32 v0, 0x4f7ffffe, v0
	v_cvt_u32_f32_e32 v0, v0
	v_ashrrev_i32_e32 v16, 6, v81
	v_bfe_u32 v80, v81, 4, 2
	v_bfe_u32 v17, v81, 3, 3
	v_readfirstlane_b32 s17, v0
	s_mul_i32 s16, s16, s17
	s_mul_hi_u32 s16, s17, s16
	s_add_i32 s17, s17, s16
	s_mul_hi_u32 s16, s13, s17
	s_mul_i32 s17, s16, s8
	s_sub_i32 s13, s13, s17
	s_add_i32 s18, s16, 1
	s_sub_i32 s17, s13, s8
	s_cmp_ge_u32 s13, s8
	s_cselect_b32 s16, s18, s16
	s_cselect_b32 s13, s17, s13
	s_add_i32 s17, s16, 1
	s_cmp_ge_u32 s13, s8
	s_cselect_b32 s13, s17, s16
	s_abs_i32 s17, s2
	v_cvt_f32_u32_e32 v0, s17
	s_xor_b32 s16, s13, s12
	s_sub_i32 s13, 0, s17
	s_sub_i32 s18, s16, s12
	v_rcp_iflag_f32_e32 v0, v0
	s_mul_i32 s3, s18, s3
	s_sub_i32 s3, s10, s3
	s_abs_i32 s28, s3
	v_mul_f32_e32 v0, 0x4f7ffffe, v0
	v_cvt_u32_f32_e32 v0, v0
	s_xor_b32 s19, s3, s2
	s_ashr_i32 s19, s19, 31
	v_lshlrev_b32_e32 v18, 5, v16
	v_readfirstlane_b32 s29, v0
	s_mul_i32 s13, s13, s29
	s_mul_hi_u32 s13, s29, s13
	s_add_i32 s29, s29, s13
	s_mul_hi_u32 s13, s28, s29
	s_mul_i32 s29, s13, s17
	s_sub_i32 s28, s28, s29
	s_add_i32 s38, s13, 1
	s_sub_i32 s29, s28, s17
	s_cmp_ge_u32 s28, s17
	s_cselect_b32 s13, s38, s13
	s_cselect_b32 s28, s29, s28
	s_add_i32 s29, s13, 1
	s_cmp_ge_u32 s28, s17
	s_cselect_b32 s13, s29, s13
	s_xor_b32 s17, s13, s19
	s_sub_i32 s13, s17, s19
	s_mul_i32 s2, s13, s2
	s_add_i32 s3, s3, s1
	s_sub_i32 s3, s3, s2
	s_lshl_b32 s2, s18, 10
	s_lshl_b32 s13, s13, 7
	v_xor_b32_e32 v0, v80, v81
	s_add_i32 s2, s13, s2
	v_or_b32_e32 v1, v18, v17
	v_lshlrev_b32_e32 v0, 3, v0
	v_add_u32_e32 v2, s2, v1
	v_and_b32_e32 v19, 56, v0
	v_or_b32_e32 v3, 8, v1
	v_lshl_or_b32 v192, v2, 10, v19
	v_lshrrev_b32_e32 v2, 1, v3
	s_lshl_b32 s13, s3, 10
	v_readlane_b32 s3, v252, 39
	v_xor_b32_e32 v2, v2, v81
	s_or_b32 s3, s13, s3
	v_lshlrev_b32_e32 v2, 3, v2
	v_add_u32_e32 v4, s2, v3
	v_and_b32_e32 v20, 56, v2
	v_add_u32_e32 v3, s3, v3
	v_lshl_or_b32 v2, v4, 10, v20
	v_lshl_or_b32 v4, v3, 10, v20
	v_or_b32_e32 v3, 16, v1
	v_add_u32_e32 v0, s3, v1
	s_waitcnt lgkmcnt(0)
	v_add_u32_e32 v5, s2, v3
	v_add_u32_e32 v3, s3, v3
	v_or_b32_e32 v1, 24, v1
	v_lshl_or_b32 v8, v3, 10, v19
	v_lshrrev_b32_e32 v3, 1, v1
	v_xor_b32_e32 v3, v3, v81
	s_cmp_lg_u32 32, -1
	v_lshlrev_b32_e32 v3, 3, v3
	v_lshlrev_b32_e32 v22, 12, v16
	s_cselect_b32 s18, 32, 0
	v_lshl_or_b32 v6, v5, 10, v19
	v_add_u32_e32 v5, s2, v1
	v_and_b32_e32 v21, 56, v3
	v_add_u32_e32 v1, s3, v1
	v_add_u32_e32 v85, s18, v22
	s_add_i32 s28, s18, 0x4000
	v_lshl_or_b32 v12, v1, 10, v21
	v_ashrrev_i32_e32 v1, 1, v81
	v_add_u32_e32 v3, s28, v22
	v_readfirstlane_b32 s28, v85
	v_lshl_or_b32 v0, v0, 10, v19
	v_and_b32_e32 v83, 0xffffffc0, v1
	v_lshl_add_u64 v[14:15], v[192:193], 1, s[96:97]
	s_mov_b32 m0, s28
	v_mov_b32_e32 v1, v193
	v_readfirstlane_b32 s28, v3
	global_load_lds_dwordx4 v[14:15], off
	v_lshl_add_u64 v[0:1], v[0:1], 1, s[74:75]
	s_mov_b32 m0, s28
	v_mov_b32_e32 v3, v193
	s_add_i32 s28, s18, 0x400
	global_load_lds_dwordx4 v[0:1], off
	v_lshl_add_u64 v[0:1], v[2:3], 1, s[96:97]
	v_add_u32_e32 v2, s28, v22
	v_lshl_or_b32 v10, v5, 10, v21
	v_readfirstlane_b32 s28, v2
	s_mov_b32 m0, s28
	s_add_i32 s28, s18, 0x4400
	v_add_u32_e32 v2, s28, v22
	global_load_lds_dwordx4 v[0:1], off
	v_readfirstlane_b32 s28, v2
	s_mov_b32 m0, s28
	s_add_i32 s28, s18, 0x800
	v_mov_b32_e32 v5, v193
	v_add_u32_e32 v2, s28, v22
	v_lshl_add_u64 v[0:1], v[4:5], 1, s[74:75]
	v_readfirstlane_b32 s28, v2
	global_load_lds_dwordx4 v[0:1], off
	s_mov_b32 m0, s28
	s_add_i32 s28, s18, 0x4800
	v_mov_b32_e32 v7, v193
	v_add_u32_e32 v2, s28, v22
	v_lshl_add_u64 v[0:1], v[6:7], 1, s[96:97]
	v_readfirstlane_b32 s28, v2
	global_load_lds_dwordx4 v[0:1], off
	s_mov_b32 m0, s28
	s_add_i32 s28, s18, 0xc00
	v_mov_b32_e32 v9, v193
	v_add_u32_e32 v2, s28, v22
	s_addk_i32 s18, 0x4c00
	v_lshl_add_u64 v[0:1], v[8:9], 1, s[74:75]
	v_mov_b32_e32 v11, v193
	v_readfirstlane_b32 s28, v2
	v_add_u32_e32 v2, s18, v22
	global_load_lds_dwordx4 v[0:1], off
	v_lshl_add_u64 v[0:1], v[10:11], 1, s[96:97]
	s_mov_b32 m0, s28
	v_mov_b32_e32 v13, v193
	v_readfirstlane_b32 s18, v2
	global_load_lds_dwordx4 v[0:1], off
	v_lshl_add_u64 v[0:1], v[12:13], 1, s[74:75]
	s_mov_b32 m0, s18
	s_lshl_b32 s18, s16, 10
	global_load_lds_dwordx4 v[0:1], off
	v_bfe_u32 v0, v81, 1, 3
	s_lshl_b32 s28, s17, 7
	v_xor_b32_e32 v1, v80, v0
	v_bitop3_b32 v0, v80, v0, 4 bitop3:0x36
	s_add_i32 s28, s28, s18
	v_lshlrev_b32_e32 v86, 4, v0
	v_or_b32_e32 v0, s28, v17
	v_add_u32_e32 v0, v0, v18
	s_lshl_b32 s18, s19, 7
	v_subrev_u32_e32 v0, s18, v0
	s_lshl_b32 s18, s12, 10
	v_subrev_u32_e32 v0, s18, v0
	s_lshl_b32 s18, s16, 20
	s_lshl_b32 s28, s17, 17
	v_lshl_or_b32 v192, v0, 10, v19
	v_lshlrev_b32_e32 v0, 15, v16
	s_add_i32 s18, s18, s28
	v_lshlrev_b32_e32 v87, 4, v1
	v_lshlrev_b32_e32 v1, 10, v17
	v_add_u32_e32 v2, s18, v0
	v_or_b32_e32 v2, v2, v1
	s_add_i32 s1, s10, s1
	s_lshl_b32 s10, s12, 3
	v_or3_b32 v3, v2, v20, s33
	s_lshl_b32 s18, s19, 17
	s_add_i32 s19, s19, s10
	v_subrev_u32_e32 v3, s18, v3
	s_lshl_b32 s28, s12, 20
	s_sub_i32 s10, s19, s17
	s_lshl_b32 s12, s16, 3
	v_lshl_add_u64 v[64:65], v[192:193], 1, s[68:69]
	v_subrev_u32_e32 v192, s28, v3
	v_or3_b32 v3, v2, v19, s30
	s_sub_i32 s10, s10, s12
	s_min_i32 s0, s0, 8
	v_subrev_u32_e32 v3, s18, v3
	v_or3_b32 v2, v2, v21, s67
	s_mul_i32 s10, s10, s0
	v_lshl_add_u64 v[66:67], v[192:193], 1, s[68:69]
	v_subrev_u32_e32 v192, s28, v3
	v_subrev_u32_e32 v2, s18, v2
	s_add_i32 s1, s1, s10
	v_lshl_add_u64 v[68:69], v[192:193], 1, s[68:69]
	v_subrev_u32_e32 v192, s28, v2
	v_add_u32_e32 v2, s31, v17
	s_lshl_b32 s0, s1, 10
	v_add3_u32 v2, v2, v18, s0
	v_lshl_add_u64 v[70:71], v[192:193], 1, s[68:69]
	v_lshl_or_b32 v192, v2, 10, v19
	v_add3_u32 v2, s58, v0, v1
	s_lshl_b32 s0, s1, 20
	v_lshl_add_u64 v[72:73], v[192:193], 1, s[56:57]
	v_add3_u32 v192, v2, v20, s0
	v_add3_u32 v2, s59, v0, v1
	v_readlane_b32 s1, v254, 34
	v_and_b32_e32 v84, 15, v81
	s_waitcnt vmcnt(0)
	v_lshl_add_u64 v[74:75], v[192:193], 1, s[56:57]
	v_add3_u32 v192, v2, v19, s0
	v_add3_u32 v0, s1, v0, v1
	v_or_b32_e32 v23, v83, v84
	v_lshlrev_b32_e32 v24, 7, v81
	v_lshl_add_u64 v[76:77], v[192:193], 1, s[56:57]
	v_add3_u32 v192, v0, v21, s0
	v_mov_b32_e32 v56, 0
	s_mov_b32 s8, 0
	v_and_b32_e32 v82, 63, v81
	v_lshlrev_b32_e32 v88, 7, v23
	v_and_b32_e32 v89, 0x2780, v24
	v_lshl_add_u64 v[78:79], v[192:193], 1, s[56:57]
	s_mov_b64 s[0:1], 0
	v_mov_b32_e32 v57, v56
	v_mov_b32_e32 v58, v56
	v_mov_b32_e32 v59, v56
	v_mov_b32_e32 v60, v56
	v_mov_b32_e32 v61, v56
	v_mov_b32_e32 v62, v56
	v_mov_b32_e32 v63, v56
	v_mov_b32_e32 v0, v56
	v_mov_b32_e32 v1, v56
	v_mov_b32_e32 v2, v56
	v_mov_b32_e32 v3, v56
	v_mov_b32_e32 v4, v56
	v_mov_b32_e32 v5, v56
	v_mov_b32_e32 v6, v56
	v_mov_b32_e32 v7, v56
	v_mov_b32_e32 v8, v56
	v_mov_b32_e32 v9, v56
	v_mov_b32_e32 v10, v56
	v_mov_b32_e32 v11, v56
	v_mov_b32_e32 v12, v56
	v_mov_b32_e32 v13, v56
	v_mov_b32_e32 v14, v56
	v_mov_b32_e32 v15, v56
	v_mov_b32_e32 v16, v56
	v_mov_b32_e32 v17, v56
	v_mov_b32_e32 v18, v56
	v_mov_b32_e32 v19, v56
	v_mov_b32_e32 v20, v56
	v_mov_b32_e32 v21, v56
	v_mov_b32_e32 v22, v56
	v_mov_b32_e32 v23, v56
	v_mov_b32_e32 v24, v56
	v_mov_b32_e32 v25, v56
	v_mov_b32_e32 v26, v56
	v_mov_b32_e32 v27, v56
	v_mov_b32_e32 v28, v56
	v_mov_b32_e32 v29, v56
	v_mov_b32_e32 v30, v56
	v_mov_b32_e32 v31, v56
	v_mov_b32_e32 v32, v56
	v_mov_b32_e32 v33, v56
	v_mov_b32_e32 v34, v56
	v_mov_b32_e32 v35, v56
	v_mov_b32_e32 v36, v56
	v_mov_b32_e32 v37, v56
	v_mov_b32_e32 v38, v56
	v_mov_b32_e32 v39, v56
	v_mov_b32_e32 v40, v56
	v_mov_b32_e32 v41, v56
	v_mov_b32_e32 v42, v56
	v_mov_b32_e32 v43, v56
	v_mov_b32_e32 v44, v56
	v_mov_b32_e32 v45, v56
	v_mov_b32_e32 v46, v56
	v_mov_b32_e32 v47, v56
	v_mov_b32_e32 v48, v56
	v_mov_b32_e32 v49, v56
	v_mov_b32_e32 v50, v56
	v_mov_b32_e32 v51, v56
	v_mov_b32_e32 v52, v56
	v_mov_b32_e32 v53, v56
	v_mov_b32_e32 v54, v56
	v_mov_b32_e32 v55, v56
	s_waitcnt vmcnt(0) lgkmcnt(0)
	s_barrier
	v_add_u32_e32 v134, 32, v88
	v_add_u32_e32 v135, 32, v89
	v_add_u32_e32 v132, v134, v87
	v_add_u32_e32 v133, v135, v87
	ds_read_b128 v[90:93], v132
	ds_read_b128 v[98:101], v132 offset:2048
	ds_read_b128 v[106:109], v132 offset:4096
	ds_read_b128 v[114:117], v132 offset:6144
	ds_read_b128 v[94:97], v133 offset:16384
	ds_read_b128 v[102:105], v133 offset:18432
	ds_read_b128 v[110:113], v133 offset:20480
	ds_read_b128 v[118:121], v133 offset:22528
	v_readfirstlane_b32 s98, v64
	v_readfirstlane_b32 s99, v65
	v_readfirstlane_b32 s100, v72
	v_readfirstlane_b32 s101, v73
	s_sub_u32 s98, s98, 0x80
	s_subb_u32 s99, s99, 0
	s_sub_u32 s100, s100, 0x80
	s_subb_u32 s101, s101, 0
	v_subrev_u32_e32 v64, s98, v64
	v_subrev_u32_e32 v66, s98, v66
	v_subrev_u32_e32 v68, s98, v68
	v_subrev_u32_e32 v70, s98, v70
	v_subrev_u32_e32 v72, s100, v72
	v_subrev_u32_e32 v74, s100, v74
	v_subrev_u32_e32 v76, s100, v76
	v_subrev_u32_e32 v78, s100, v78
	v_add_u32_e32 v128, 0x8000, v85
	s_nop 0
	v_readfirstlane_b32 s12, v128
	s_nop 1
	s_mov_b32 m0, s12
	s_nop 0
	global_load_lds_dwordx4 v64, s[98:99]
	s_add_i32 m0, s12, 0x4000
	s_nop 0
	global_load_lds_dwordx4 v72, s[100:101]
	s_add_i32 m0, s12, 0x400
	s_nop 0
	global_load_lds_dwordx4 v66, s[98:99]
	s_add_i32 m0, s12, 0x4400
	s_nop 0
	global_load_lds_dwordx4 v74, s[100:101]
	s_add_i32 m0, s12, 0x800
	s_nop 0
	global_load_lds_dwordx4 v68, s[98:99]
	s_add_i32 m0, s12, 0x4800
	s_nop 0
	global_load_lds_dwordx4 v76, s[100:101]
	s_add_i32 m0, s12, 0xc00
	s_nop 0
	global_load_lds_dwordx4 v70, s[98:99]
	s_add_i32 m0, s12, 0x4c00
	s_nop 0
	global_load_lds_dwordx4 v78, s[100:101]
	s_add_u32 s0, s0, 0x80
	s_addc_u32 s1, s1, 0
	s_add_u32 s98, s98, 0x80
	s_addc_u32 s99, s99, 0
	s_add_u32 s100, s100, 0x80
	s_addc_u32 s101, s101, 0
	.p2align 6
